# softmax epilogue rewritten: exps computed once in place, P=e*rcp(sum) instead of second exp pass, batched butterfly reduce (2 waits instead of 16)
# speedup vs baseline: 1.0208x; 1.0003x over previous
; #define LAS __attribute__((address_space(3)))
; __device__ __forceinline__ void epi_softmax(const f32x4 (&acc)[2][2][4][2], const Unit& u, char* Cb, unsigned cZ1, unsigned cZ2, int ldc, LAS float* rs, int wr, int wc, int fr, int fq) {
; #pragma unroll
;     for (int ai = 0; ai < 2; ++ai)
; #pragma unroll
;         for (int m = 0; m < 4; ++m) { float s = 0.f;
; #pragma unroll
;             for (int bj = 0; bj < 2; ++bj)
; #pragma unroll
;                 for (int n = 0; n < 2; ++n)
; #pragma unroll
;                     for (int j = 0; j < 4; ++j) s += __expf(acc[ai][bj][m][n][j]);
;             s += __shfl_xor(s, 16, 64); s += __shfl_xor(s, 32, 64);
;             if (fq == 0) rs[((wr * 128 + ai * 64 + m * 16 + fr) << 2) + wc] = s; }
.LBB0_525:
	s_and_b64 vcc, exec, s[2:3]
	s_cbranch_vccz .LBB0_543
	s_load_dwordx2 s[8:9], s[90:91], 0x1f8
	s_load_dword s2, s[90:91], 0x228
	v_cmp_lt_i32_e32 vcc, v215, v219
	v_readlane_b32 s3, v255, 6
	s_nop 1
	v_cndmask_b32_e32 v10, v213, v215, vcc
	v_cmp_lt_i32_e32 vcc, v230, v219
	v_lshlrev_b32_e32 v10, 2, v10
	v_add_u32_e32 v135, s3, v235
	v_cndmask_b32_e32 v12, v213, v230, vcc
	v_lshlrev_b32_e32 v12, 2, v12
	v_mul_f32_e32 v130, 0x3fb8aa3b, v130
	v_mul_f32_e32 v131, 0x3fb8aa3b, v131
	v_mul_f32_e32 v132, 0x3fb8aa3b, v132
	v_mul_f32_e32 v133, 0x3fb8aa3b, v133
	v_mul_f32_e32 v126, 0x3fb8aa3b, v126
	v_mul_f32_e32 v127, 0x3fb8aa3b, v127
	v_mul_f32_e32 v128, 0x3fb8aa3b, v128
	v_mul_f32_e32 v129, 0x3fb8aa3b, v129
	v_mul_f32_e32 v122, 0x3fb8aa3b, v122
	v_mul_f32_e32 v123, 0x3fb8aa3b, v123
	v_mul_f32_e32 v124, 0x3fb8aa3b, v124
	v_mul_f32_e32 v125, 0x3fb8aa3b, v125
	v_mul_f32_e32 v118, 0x3fb8aa3b, v118
	v_mul_f32_e32 v119, 0x3fb8aa3b, v119
	v_mul_f32_e32 v120, 0x3fb8aa3b, v120
	v_mul_f32_e32 v121, 0x3fb8aa3b, v121
	v_exp_f32_e32 v130, v130
	v_exp_f32_e32 v131, v131
	v_exp_f32_e32 v132, v132
	v_exp_f32_e32 v133, v133
	v_exp_f32_e32 v126, v126
	v_exp_f32_e32 v127, v127
	v_exp_f32_e32 v128, v128
	v_exp_f32_e32 v129, v129
	v_exp_f32_e32 v122, v122
	v_exp_f32_e32 v123, v123
	v_exp_f32_e32 v124, v124
	v_exp_f32_e32 v125, v125
	v_exp_f32_e32 v118, v118
	v_exp_f32_e32 v119, v119
	v_exp_f32_e32 v120, v120
	v_exp_f32_e32 v121, v121
	v_add_f32_e32 v136, v130, v132
	v_add_f32_e32 v144, v131, v133
	v_add_f32_e32 v136, v126, v136
	v_add_f32_e32 v144, v127, v144
	v_add_f32_e32 v136, v128, v136
	v_add_f32_e32 v144, v129, v144
	v_add_f32_e32 v136, v122, v136
	v_add_f32_e32 v144, v123, v144
	v_add_f32_e32 v136, v124, v136
	v_add_f32_e32 v144, v125, v144
	v_add_f32_e32 v136, v118, v136
	v_add_f32_e32 v144, v119, v144
	v_add_f32_e32 v136, v120, v136
	v_add_f32_e32 v144, v121, v144
	v_add_f32_e32 v136, v136, v144
	v_mul_f32_e32 v114, 0x3fb8aa3b, v114
	v_mul_f32_e32 v115, 0x3fb8aa3b, v115
	v_mul_f32_e32 v116, 0x3fb8aa3b, v116
	v_mul_f32_e32 v117, 0x3fb8aa3b, v117
	v_mul_f32_e32 v110, 0x3fb8aa3b, v110
	v_mul_f32_e32 v111, 0x3fb8aa3b, v111
	v_mul_f32_e32 v112, 0x3fb8aa3b, v112
	v_mul_f32_e32 v113, 0x3fb8aa3b, v113
	v_mul_f32_e32 v106, 0x3fb8aa3b, v106
	v_mul_f32_e32 v107, 0x3fb8aa3b, v107
	v_mul_f32_e32 v108, 0x3fb8aa3b, v108
	v_mul_f32_e32 v109, 0x3fb8aa3b, v109
	v_mul_f32_e32 v102, 0x3fb8aa3b, v102
	v_mul_f32_e32 v103, 0x3fb8aa3b, v103
	v_mul_f32_e32 v104, 0x3fb8aa3b, v104
	v_mul_f32_e32 v105, 0x3fb8aa3b, v105
	v_exp_f32_e32 v114, v114
	v_exp_f32_e32 v115, v115
	v_exp_f32_e32 v116, v116
	v_exp_f32_e32 v117, v117
	v_exp_f32_e32 v110, v110
	v_exp_f32_e32 v111, v111
	v_exp_f32_e32 v112, v112
	v_exp_f32_e32 v113, v113
	v_exp_f32_e32 v106, v106
	v_exp_f32_e32 v107, v107
	v_exp_f32_e32 v108, v108
	v_exp_f32_e32 v109, v109
	v_exp_f32_e32 v102, v102
	v_exp_f32_e32 v103, v103
	v_exp_f32_e32 v104, v104
	v_exp_f32_e32 v105, v105
	v_add_f32_e32 v137, v114, v116
	v_add_f32_e32 v145, v115, v117
	v_add_f32_e32 v137, v110, v137
	v_add_f32_e32 v145, v111, v145
	v_add_f32_e32 v137, v112, v137
	v_add_f32_e32 v145, v113, v145
	v_add_f32_e32 v137, v106, v137
	v_add_f32_e32 v145, v107, v145
	v_add_f32_e32 v137, v108, v137
	v_add_f32_e32 v145, v109, v145
	v_add_f32_e32 v137, v102, v137
	v_add_f32_e32 v145, v103, v145
	v_add_f32_e32 v137, v104, v137
	v_add_f32_e32 v145, v105, v145
	v_add_f32_e32 v137, v137, v145
	v_mul_f32_e32 v98, 0x3fb8aa3b, v98
	v_mul_f32_e32 v99, 0x3fb8aa3b, v99
	v_mul_f32_e32 v100, 0x3fb8aa3b, v100
	v_mul_f32_e32 v101, 0x3fb8aa3b, v101
	v_mul_f32_e32 v94, 0x3fb8aa3b, v94
	v_mul_f32_e32 v95, 0x3fb8aa3b, v95
	v_mul_f32_e32 v96, 0x3fb8aa3b, v96
	v_mul_f32_e32 v97, 0x3fb8aa3b, v97
	v_mul_f32_e32 v90, 0x3fb8aa3b, v90
	v_mul_f32_e32 v91, 0x3fb8aa3b, v91
	v_mul_f32_e32 v92, 0x3fb8aa3b, v92
	v_mul_f32_e32 v93, 0x3fb8aa3b, v93
	v_mul_f32_e32 v86, 0x3fb8aa3b, v86
	v_mul_f32_e32 v87, 0x3fb8aa3b, v87
	v_mul_f32_e32 v88, 0x3fb8aa3b, v88
	v_mul_f32_e32 v89, 0x3fb8aa3b, v89
	v_exp_f32_e32 v98, v98
	v_exp_f32_e32 v99, v99
	v_exp_f32_e32 v100, v100
	v_exp_f32_e32 v101, v101
	v_exp_f32_e32 v94, v94
	v_exp_f32_e32 v95, v95
	v_exp_f32_e32 v96, v96
	v_exp_f32_e32 v97, v97
	v_exp_f32_e32 v90, v90
	v_exp_f32_e32 v91, v91
	v_exp_f32_e32 v92, v92
	v_exp_f32_e32 v93, v93
	v_exp_f32_e32 v86, v86
	v_exp_f32_e32 v87, v87
	v_exp_f32_e32 v88, v88
	v_exp_f32_e32 v89, v89
	v_add_f32_e32 v138, v98, v100
	v_add_f32_e32 v146, v99, v101
	v_add_f32_e32 v138, v94, v138
	v_add_f32_e32 v146, v95, v146
	v_add_f32_e32 v138, v96, v138
	v_add_f32_e32 v146, v97, v146
	v_add_f32_e32 v138, v90, v138
	v_add_f32_e32 v146, v91, v146
	v_add_f32_e32 v138, v92, v138
	v_add_f32_e32 v146, v93, v146
	v_add_f32_e32 v138, v86, v138
	v_add_f32_e32 v146, v87, v146
	v_add_f32_e32 v138, v88, v138
	v_add_f32_e32 v146, v89, v146
	v_add_f32_e32 v138, v138, v146
	v_mul_f32_e32 v82, 0x3fb8aa3b, v82
	v_mul_f32_e32 v83, 0x3fb8aa3b, v83
	v_mul_f32_e32 v84, 0x3fb8aa3b, v84
	v_mul_f32_e32 v85, 0x3fb8aa3b, v85
	v_mul_f32_e32 v78, 0x3fb8aa3b, v78
	v_mul_f32_e32 v79, 0x3fb8aa3b, v79
	v_mul_f32_e32 v80, 0x3fb8aa3b, v80
	v_mul_f32_e32 v81, 0x3fb8aa3b, v81
	v_mul_f32_e32 v74, 0x3fb8aa3b, v74
	v_mul_f32_e32 v75, 0x3fb8aa3b, v75
	v_mul_f32_e32 v76, 0x3fb8aa3b, v76
	v_mul_f32_e32 v77, 0x3fb8aa3b, v77
	v_mul_f32_e32 v70, 0x3fb8aa3b, v70
	v_mul_f32_e32 v71, 0x3fb8aa3b, v71
	v_mul_f32_e32 v72, 0x3fb8aa3b, v72
	v_mul_f32_e32 v73, 0x3fb8aa3b, v73
	v_exp_f32_e32 v82, v82
	v_exp_f32_e32 v83, v83
	v_exp_f32_e32 v84, v84
	v_exp_f32_e32 v85, v85
	v_exp_f32_e32 v78, v78
	v_exp_f32_e32 v79, v79
	v_exp_f32_e32 v80, v80
	v_exp_f32_e32 v81, v81
	v_exp_f32_e32 v74, v74
; __device__ __forceinline__ void epi_softmax(const f32x4 (&acc)[2][2][4][2], const Unit& u, char* Cb, unsigned cZ1, unsigned cZ2, int ldc, LAS float* rs, int wr, int wc, int fr, int fq) {
;     ...
;         for (int m = 0; m < 4; ++m) { float s = 0.f;
; #pragma unroll
;             for (int bj = 0; bj < 2; ++bj)
; #pragma unroll
;                 for (int n = 0; n < 2; ++n)
; #pragma unroll
;                     for (int j = 0; j < 4; ++j) s += __expf(acc[ai][bj][m][n][j]);
;             s += __shfl_xor(s, 16, 64); s += __shfl_xor(s, 32, 64);
	v_exp_f32_e32 v75, v75
	v_exp_f32_e32 v76, v76
	v_exp_f32_e32 v77, v77
	v_exp_f32_e32 v70, v70
	v_exp_f32_e32 v71, v71
	v_exp_f32_e32 v72, v72
	v_exp_f32_e32 v73, v73
	v_add_f32_e32 v139, v82, v84
	v_add_f32_e32 v147, v83, v85
	v_add_f32_e32 v139, v78, v139
	v_add_f32_e32 v147, v79, v147
	v_add_f32_e32 v139, v80, v139
	v_add_f32_e32 v147, v81, v147
	v_add_f32_e32 v139, v74, v139
	v_add_f32_e32 v147, v75, v147
	v_add_f32_e32 v139, v76, v139
	v_add_f32_e32 v147, v77, v147
	v_add_f32_e32 v139, v70, v139
	v_add_f32_e32 v147, v71, v147
	v_add_f32_e32 v139, v72, v139
	v_add_f32_e32 v147, v73, v147
	v_add_f32_e32 v139, v139, v147
	v_mul_f32_e32 v66, 0x3fb8aa3b, v66
	v_mul_f32_e32 v67, 0x3fb8aa3b, v67
	v_mul_f32_e32 v68, 0x3fb8aa3b, v68
	v_mul_f32_e32 v69, 0x3fb8aa3b, v69
	v_mul_f32_e32 v62, 0x3fb8aa3b, v62
	v_mul_f32_e32 v63, 0x3fb8aa3b, v63
	v_mul_f32_e32 v64, 0x3fb8aa3b, v64
	v_mul_f32_e32 v65, 0x3fb8aa3b, v65
	v_mul_f32_e32 v58, 0x3fb8aa3b, v58
	v_mul_f32_e32 v59, 0x3fb8aa3b, v59
	v_mul_f32_e32 v60, 0x3fb8aa3b, v60
	v_mul_f32_e32 v61, 0x3fb8aa3b, v61
	v_mul_f32_e32 v54, 0x3fb8aa3b, v54
	v_mul_f32_e32 v55, 0x3fb8aa3b, v55
	v_mul_f32_e32 v56, 0x3fb8aa3b, v56
	v_mul_f32_e32 v57, 0x3fb8aa3b, v57
	v_exp_f32_e32 v66, v66
	v_exp_f32_e32 v67, v67
	v_exp_f32_e32 v68, v68
	v_exp_f32_e32 v69, v69
	v_exp_f32_e32 v62, v62
	v_exp_f32_e32 v63, v63
	v_exp_f32_e32 v64, v64
	v_exp_f32_e32 v65, v65
	v_exp_f32_e32 v58, v58
	v_exp_f32_e32 v59, v59
	v_exp_f32_e32 v60, v60
	v_exp_f32_e32 v61, v61
	v_exp_f32_e32 v54, v54
	v_exp_f32_e32 v55, v55
	v_exp_f32_e32 v56, v56
	v_exp_f32_e32 v57, v57
	v_add_f32_e32 v140, v66, v68
	v_add_f32_e32 v148, v67, v69
	v_add_f32_e32 v140, v62, v140
	v_add_f32_e32 v148, v63, v148
	v_add_f32_e32 v140, v64, v140
	v_add_f32_e32 v148, v65, v148
	v_add_f32_e32 v140, v58, v140
	v_add_f32_e32 v148, v59, v148
	v_add_f32_e32 v140, v60, v140
	v_add_f32_e32 v148, v61, v148
	v_add_f32_e32 v140, v54, v140
	v_add_f32_e32 v148, v55, v148
	v_add_f32_e32 v140, v56, v140
	v_add_f32_e32 v148, v57, v148
	v_add_f32_e32 v140, v140, v148
	v_mul_f32_e32 v50, 0x3fb8aa3b, v50
	v_mul_f32_e32 v51, 0x3fb8aa3b, v51
	v_mul_f32_e32 v52, 0x3fb8aa3b, v52
	v_mul_f32_e32 v53, 0x3fb8aa3b, v53
	v_mul_f32_e32 v46, 0x3fb8aa3b, v46
	v_mul_f32_e32 v47, 0x3fb8aa3b, v47
	v_mul_f32_e32 v48, 0x3fb8aa3b, v48
	v_mul_f32_e32 v49, 0x3fb8aa3b, v49
	v_mul_f32_e32 v42, 0x3fb8aa3b, v42
	v_mul_f32_e32 v43, 0x3fb8aa3b, v43
	v_mul_f32_e32 v44, 0x3fb8aa3b, v44
	v_mul_f32_e32 v45, 0x3fb8aa3b, v45
	v_mul_f32_e32 v38, 0x3fb8aa3b, v38
	v_mul_f32_e32 v39, 0x3fb8aa3b, v39
	v_mul_f32_e32 v40, 0x3fb8aa3b, v40
	v_mul_f32_e32 v41, 0x3fb8aa3b, v41
	v_exp_f32_e32 v50, v50
	v_exp_f32_e32 v51, v51
	v_exp_f32_e32 v52, v52
	v_exp_f32_e32 v53, v53
	v_exp_f32_e32 v46, v46
	v_exp_f32_e32 v47, v47
	v_exp_f32_e32 v48, v48
	v_exp_f32_e32 v49, v49
	v_exp_f32_e32 v42, v42
	v_exp_f32_e32 v43, v43
	v_exp_f32_e32 v44, v44
	v_exp_f32_e32 v45, v45
	v_exp_f32_e32 v38, v38
	v_exp_f32_e32 v39, v39
	v_exp_f32_e32 v40, v40
	v_exp_f32_e32 v41, v41
	v_add_f32_e32 v141, v50, v52
	v_add_f32_e32 v149, v51, v53
	v_add_f32_e32 v141, v46, v141
	v_add_f32_e32 v149, v47, v149
	v_add_f32_e32 v141, v48, v141
	v_add_f32_e32 v149, v49, v149
	v_add_f32_e32 v141, v42, v141
	v_add_f32_e32 v149, v43, v149
	v_add_f32_e32 v141, v44, v141
	v_add_f32_e32 v149, v45, v149
	v_add_f32_e32 v141, v38, v141
	v_add_f32_e32 v149, v39, v149
	v_add_f32_e32 v141, v40, v141
	v_add_f32_e32 v149, v41, v149
	v_add_f32_e32 v141, v141, v149
	v_mul_f32_e32 v34, 0x3fb8aa3b, v34
	v_mul_f32_e32 v35, 0x3fb8aa3b, v35
	v_mul_f32_e32 v36, 0x3fb8aa3b, v36
	v_mul_f32_e32 v37, 0x3fb8aa3b, v37
	v_mul_f32_e32 v30, 0x3fb8aa3b, v30
	v_mul_f32_e32 v31, 0x3fb8aa3b, v31
	v_mul_f32_e32 v32, 0x3fb8aa3b, v32
	v_mul_f32_e32 v33, 0x3fb8aa3b, v33
	v_mul_f32_e32 v26, 0x3fb8aa3b, v26
	v_mul_f32_e32 v27, 0x3fb8aa3b, v27
	v_mul_f32_e32 v28, 0x3fb8aa3b, v28
	v_mul_f32_e32 v29, 0x3fb8aa3b, v29
	v_mul_f32_e32 v22, 0x3fb8aa3b, v22
	v_mul_f32_e32 v23, 0x3fb8aa3b, v23
	v_mul_f32_e32 v24, 0x3fb8aa3b, v24
	v_mul_f32_e32 v25, 0x3fb8aa3b, v25
	v_exp_f32_e32 v34, v34
	v_exp_f32_e32 v35, v35
	v_exp_f32_e32 v36, v36
	v_exp_f32_e32 v37, v37
	v_exp_f32_e32 v30, v30
	v_exp_f32_e32 v31, v31
	v_exp_f32_e32 v32, v32
	v_exp_f32_e32 v33, v33
	v_exp_f32_e32 v26, v26
	v_exp_f32_e32 v27, v27
	v_exp_f32_e32 v28, v28
	v_exp_f32_e32 v29, v29
	v_exp_f32_e32 v22, v22
	v_exp_f32_e32 v23, v23
	v_exp_f32_e32 v24, v24
	v_exp_f32_e32 v25, v25
	v_add_f32_e32 v142, v34, v36
	v_add_f32_e32 v150, v35, v37
	v_add_f32_e32 v142, v30, v142
	v_add_f32_e32 v150, v31, v150
	v_add_f32_e32 v142, v32, v142
	v_add_f32_e32 v150, v33, v150
	v_add_f32_e32 v142, v26, v142
	v_add_f32_e32 v150, v27, v150
	v_add_f32_e32 v142, v28, v142
	v_add_f32_e32 v150, v29, v150
	v_add_f32_e32 v142, v22, v142
	v_add_f32_e32 v150, v23, v150
	v_add_f32_e32 v142, v24, v142
	v_add_f32_e32 v150, v25, v150
	v_add_f32_e32 v142, v142, v150
	v_mul_f32_e32 v18, 0x3fb8aa3b, v18
	v_mul_f32_e32 v19, 0x3fb8aa3b, v19
	v_mul_f32_e32 v20, 0x3fb8aa3b, v20
	v_mul_f32_e32 v21, 0x3fb8aa3b, v21
	v_mul_f32_e32 v14, 0x3fb8aa3b, v14
	v_mul_f32_e32 v15, 0x3fb8aa3b, v15
	v_mul_f32_e32 v16, 0x3fb8aa3b, v16
	v_mul_f32_e32 v17, 0x3fb8aa3b, v17
	v_mul_f32_e32 v4, 0x3fb8aa3b, v4
	v_mul_f32_e32 v5, 0x3fb8aa3b, v5
	v_mul_f32_e32 v6, 0x3fb8aa3b, v6
	v_mul_f32_e32 v7, 0x3fb8aa3b, v7
	v_mul_f32_e32 v0, 0x3fb8aa3b, v0
	v_mul_f32_e32 v1, 0x3fb8aa3b, v1
	v_mul_f32_e32 v2, 0x3fb8aa3b, v2
	v_mul_f32_e32 v3, 0x3fb8aa3b, v3
	v_exp_f32_e32 v18, v18
	v_exp_f32_e32 v19, v19
	v_exp_f32_e32 v20, v20
	v_exp_f32_e32 v21, v21
	v_exp_f32_e32 v14, v14
	v_exp_f32_e32 v15, v15
	v_exp_f32_e32 v16, v16
	v_exp_f32_e32 v17, v17
	v_exp_f32_e32 v4, v4
	v_exp_f32_e32 v5, v5
	v_exp_f32_e32 v6, v6
	v_exp_f32_e32 v7, v7
	v_exp_f32_e32 v0, v0
	v_exp_f32_e32 v1, v1
	v_exp_f32_e32 v2, v2
	v_exp_f32_e32 v3, v3
	v_add_f32_e32 v143, v18, v20
	v_add_f32_e32 v151, v19, v21
	v_add_f32_e32 v143, v14, v143
	v_add_f32_e32 v151, v15, v151
	v_add_f32_e32 v143, v16, v143
	v_add_f32_e32 v151, v17, v151
	v_add_f32_e32 v143, v4, v143
	v_add_f32_e32 v151, v5, v151
	v_add_f32_e32 v143, v6, v143
	v_add_f32_e32 v151, v7, v151
	v_add_f32_e32 v143, v0, v143
	v_add_f32_e32 v151, v1, v151
	v_add_f32_e32 v143, v2, v143
	v_add_f32_e32 v151, v3, v151
	v_add_f32_e32 v143, v143, v151
	ds_bpermute_b32 v144, v10, v136
	ds_bpermute_b32 v145, v10, v137
	ds_bpermute_b32 v146, v10, v138
	ds_bpermute_b32 v147, v10, v139
	ds_bpermute_b32 v148, v10, v140
	ds_bpermute_b32 v149, v10, v141
	ds_bpermute_b32 v150, v10, v142
	ds_bpermute_b32 v151, v10, v143
	s_waitcnt lgkmcnt(0)
; #define LAS __attribute__((address_space(3)))
; __device__ __forceinline__ unsigned cvt_pk_bf16(float lo, float hi) { unsigned r; asm volatile("v_cvt_pk_bf16_f32 %0, %1, %2" : "=v"(r) : "v"(lo), "v"(hi)); return r; }
; __device__ __forceinline__ void epi_softmax(const f32x4 (&acc)[2][2][4][2], const Unit& u, char* Cb, unsigned cZ1, unsigned cZ2, int ldc, LAS float* rs, int wr, int wc, int fr, int fq) {
;     ...
;             s += __shfl_xor(s, 16, 64); s += __shfl_xor(s, 32, 64);
;             if (fq == 0) rs[((wr * 128 + ai * 64 + m * 16 + fr) << 2) + wc] = s; }
;     asm volatile("s_waitcnt lgkmcnt(0)" ::: "memory");
;     __builtin_amdgcn_s_barrier();
;     __builtin_amdgcn_sched_barrier(0);
;     asm volatile("" : "+s"(ldc) :: "memory");
;     bf16_t* base = (bf16_t*)(Cb + (size_t)u.z1 * cZ1 + (size_t)u.z2 * cZ2) + (long)(u.pm * BM + wr * 64 + fr) * ldc + u.pn * BM + wc * 32 + 8 * fq;
; #pragma unroll
;     for (int ai = 0; ai < 2; ++ai)
; #pragma unroll
;         for (int m = 0; m < 4; ++m) {
;             const f32x4 t = *(const LAS f32x4*)&rs[(wr * 128 + ai * 64 + m * 16 + fr) << 2];
;             const float lg = __logf(t[0] + t[1] + t[2] + t[3]);
;             bf16_t* rowp = base + (long)(ai * HALF + m * 16) * ldc;
; #pragma unroll
;             for (int bj = 0; bj < 2; ++bj) { f32x4 v0, v1;
; #pragma unroll
;                 for (int j = 0; j < 4; ++j) { v0[j] = __expf(acc[ai][bj][m][0][j] - lg); v1[j] = __expf(acc[ai][bj][m][1][j] - lg); }
;                 u32x4 w; w.x = cvt_pk_bf16(v0[0], v0[1]); w.y = cvt_pk_bf16(v0[2], v0[3]); w.z = cvt_pk_bf16(v1[0], v1[1]); w.w = cvt_pk_bf16(v1[2], v1[3]);
;                 *(u32x4*)(rowp + bj * HALF) = w; } }
	v_add_f32_e32 v136, v136, v144
	v_add_f32_e32 v137, v137, v145
	v_add_f32_e32 v138, v138, v146
	v_add_f32_e32 v139, v139, v147
	v_add_f32_e32 v140, v140, v148
	v_add_f32_e32 v141, v141, v149
	v_add_f32_e32 v142, v142, v150
	v_add_f32_e32 v143, v143, v151
	ds_bpermute_b32 v144, v12, v136
	ds_bpermute_b32 v145, v12, v137
	ds_bpermute_b32 v146, v12, v138
	ds_bpermute_b32 v147, v12, v139
	ds_bpermute_b32 v148, v12, v140
	ds_bpermute_b32 v149, v12, v141
	ds_bpermute_b32 v150, v12, v142
	ds_bpermute_b32 v151, v12, v143
	s_waitcnt lgkmcnt(0)
	v_add_f32_e32 v136, v136, v144
	v_add_f32_e32 v137, v137, v145
	v_add_f32_e32 v138, v138, v146
	v_add_f32_e32 v139, v139, v147
	v_add_f32_e32 v140, v140, v148
	v_add_f32_e32 v141, v141, v149
	v_add_f32_e32 v142, v142, v150
	v_add_f32_e32 v143, v143, v151
	s_and_saveexec_b64 s[12:13], s[16:17]
	ds_write_b32 v135, v136
	ds_write_b32 v135, v137 offset:256
	ds_write_b32 v135, v138 offset:512
	ds_write_b32 v135, v139 offset:768
	ds_write_b32 v135, v140 offset:1024
	ds_write_b32 v135, v141 offset:1280
	ds_write_b32 v135, v142 offset:1536
	ds_write_b32 v135, v143 offset:1792
	s_or_b64 exec, exec, s[12:13]
	s_waitcnt lgkmcnt(0)
	s_barrier
	s_ashr_i32 s3, s18, 31
	s_mul_hi_u32 s12, s8, s18
	s_mul_i32 s3, s8, s3
	s_add_i32 s12, s12, s3
	s_mul_i32 s3, s8, s18
	s_add_u32 s3, s46, s3
	s_addc_u32 s12, s47, s12
	s_ashr_i32 s8, s26, 31
	s_mul_hi_u32 s13, s9, s26
	s_mul_i32 s8, s9, s8
	s_add_i32 s13, s13, s8
	s_mul_i32 s8, s9, s26
	s_add_u32 s8, s3, s8
	v_lshl_add_u32 v10, s68, 8, v166
	s_addc_u32 s9, s12, s13
	v_mad_i64_i32 v[12:13], s[12:13], s2, v10, 0
	v_lshl_add_u64 v[12:13], v[12:13], 1, s[8:9]
	s_lshl_b32 s8, s61, 8
	s_ashr_i32 s9, s8, 31
	v_lshl_add_u64 v[12:13], s[8:9], 1, v[12:13]
	v_readlane_b32 s8, v255, 17
	s_mov_b32 s9, s49
	s_lshl_b32 s8, s8, 1
	v_lshl_add_u64 v[12:13], v[12:13], 0, s[8:9]
	v_lshlrev_b32_e32 v10, 1, v168
	v_readlane_b32 s8, v255, 7
	v_lshl_add_u64 v[12:13], v[12:13], 0, v[10:11]
	s_nop 0
	v_add_u32_e32 v10, s8, v235
	s_ashr_i32 s3, s2, 31
	s_lshl_b64 s[8:9], s[2:3], 5
	s_mul_hi_i32 s13, s2, 0xa0
	s_mul_i32 s12, s2, 0xa0
	ds_read_b128 v[136:139], v10
	ds_read_b128 v[140:143], v10 offset:256
	ds_read_b128 v[144:147], v10 offset:512
	ds_read_b128 v[148:151], v10 offset:768
	s_waitcnt lgkmcnt(0)
	v_add_f32_e32 v136, v136, v137
	v_add_f32_e32 v136, v138, v136
	v_add_f32_e32 v136, v139, v136
	v_add_f32_e32 v140, v140, v141
	v_add_f32_e32 v140, v142, v140
	v_add_f32_e32 v140, v143, v140
	v_add_f32_e32 v144, v144, v145
	v_add_f32_e32 v144, v146, v144
	v_add_f32_e32 v144, v147, v144
	v_add_f32_e32 v148, v148, v149
	v_add_f32_e32 v148, v150, v148
	v_add_f32_e32 v148, v151, v148
	v_rcp_f32_e32 v152, v136
	v_rcp_f32_e32 v153, v140
	v_rcp_f32_e32 v154, v144
	v_rcp_f32_e32 v155, v148
	s_nop 0
	v_mul_f32_e32 v130, v130, v152
	v_mul_f32_e32 v131, v131, v152
	v_mul_f32_e32 v132, v132, v152
	v_mul_f32_e32 v133, v133, v152
	v_mul_f32_e32 v126, v126, v152
	v_mul_f32_e32 v127, v127, v152
	v_mul_f32_e32 v128, v128, v152
	v_mul_f32_e32 v129, v129, v152
	v_mul_f32_e32 v122, v122, v152
	v_mul_f32_e32 v123, v123, v152
	v_mul_f32_e32 v124, v124, v152
	v_mul_f32_e32 v125, v125, v152
	v_mul_f32_e32 v118, v118, v152
	v_mul_f32_e32 v119, v119, v152
	v_mul_f32_e32 v120, v120, v152
	v_mul_f32_e32 v121, v121, v152
	v_cvt_pk_bf16_f32 v130, v130, v131
	v_cvt_pk_bf16_f32 v131, v132, v133
	v_cvt_pk_bf16_f32 v132, v126, v127
	v_cvt_pk_bf16_f32 v133, v128, v129
	global_store_dwordx4 v[12:13], v[130:133], off
	v_cvt_pk_bf16_f32 v122, v122, v123
	v_cvt_pk_bf16_f32 v123, v124, v125
	v_cvt_pk_bf16_f32 v124, v118, v119
	v_cvt_pk_bf16_f32 v125, v120, v121
	global_store_dwordx4 v[12:13], v[122:125], off offset:256
	v_lshl_add_u64 v[12:13], v[12:13], 0, s[8:9]
	v_mul_f32_e32 v114, v114, v153
	v_mul_f32_e32 v115, v115, v153
	v_mul_f32_e32 v116, v116, v153
	v_mul_f32_e32 v117, v117, v153
	v_mul_f32_e32 v110, v110, v153
	v_mul_f32_e32 v111, v111, v153
	v_mul_f32_e32 v112, v112, v153
	v_mul_f32_e32 v113, v113, v153
	v_mul_f32_e32 v106, v106, v153
	v_mul_f32_e32 v107, v107, v153
	v_mul_f32_e32 v108, v108, v153
	v_mul_f32_e32 v109, v109, v153
	v_mul_f32_e32 v102, v102, v153
	v_mul_f32_e32 v103, v103, v153
	v_mul_f32_e32 v104, v104, v153
	v_mul_f32_e32 v105, v105, v153
	v_cvt_pk_bf16_f32 v114, v114, v115
	v_cvt_pk_bf16_f32 v115, v116, v117
	v_cvt_pk_bf16_f32 v116, v110, v111
	v_cvt_pk_bf16_f32 v117, v112, v113
	global_store_dwordx4 v[12:13], v[114:117], off
	v_cvt_pk_bf16_f32 v106, v106, v107
	v_cvt_pk_bf16_f32 v107, v108, v109
	v_cvt_pk_bf16_f32 v108, v102, v103
	v_cvt_pk_bf16_f32 v109, v104, v105
	global_store_dwordx4 v[12:13], v[106:109], off offset:256
	v_lshl_add_u64 v[12:13], v[12:13], 0, s[8:9]
	v_mul_f32_e32 v98, v98, v154
	v_mul_f32_e32 v99, v99, v154
	v_mul_f32_e32 v100, v100, v154
	v_mul_f32_e32 v101, v101, v154
	v_mul_f32_e32 v94, v94, v154
	v_mul_f32_e32 v95, v95, v154
	v_mul_f32_e32 v96, v96, v154
	v_mul_f32_e32 v97, v97, v154
	v_mul_f32_e32 v90, v90, v154
	v_mul_f32_e32 v91, v91, v154
	v_mul_f32_e32 v92, v92, v154
	v_mul_f32_e32 v93, v93, v154
	v_mul_f32_e32 v86, v86, v154
	v_mul_f32_e32 v87, v87, v154
	v_mul_f32_e32 v88, v88, v154
	v_mul_f32_e32 v89, v89, v154
	v_cvt_pk_bf16_f32 v98, v98, v99
	v_cvt_pk_bf16_f32 v99, v100, v101
	v_cvt_pk_bf16_f32 v100, v94, v95
	v_cvt_pk_bf16_f32 v101, v96, v97
	global_store_dwordx4 v[12:13], v[98:101], off
	v_cvt_pk_bf16_f32 v90, v90, v91
	v_cvt_pk_bf16_f32 v91, v92, v93
	v_cvt_pk_bf16_f32 v92, v86, v87
	v_cvt_pk_bf16_f32 v93, v88, v89
	global_store_dwordx4 v[12:13], v[90:93], off offset:256
	v_lshl_add_u64 v[12:13], v[12:13], 0, s[8:9]
	v_mul_f32_e32 v82, v82, v155
	v_mul_f32_e32 v83, v83, v155
	v_mul_f32_e32 v84, v84, v155
	v_mul_f32_e32 v85, v85, v155
	v_mul_f32_e32 v78, v78, v155
	v_mul_f32_e32 v79, v79, v155
	v_mul_f32_e32 v80, v80, v155
	v_mul_f32_e32 v81, v81, v155
	v_mul_f32_e32 v74, v74, v155
	v_mul_f32_e32 v75, v75, v155
	v_mul_f32_e32 v76, v76, v155
	v_mul_f32_e32 v77, v77, v155
	v_mul_f32_e32 v70, v70, v155
	v_mul_f32_e32 v71, v71, v155
	v_mul_f32_e32 v72, v72, v155
	v_mul_f32_e32 v73, v73, v155
	v_cvt_pk_bf16_f32 v82, v82, v83
	v_cvt_pk_bf16_f32 v83, v84, v85
	v_cvt_pk_bf16_f32 v84, v78, v79
	v_cvt_pk_bf16_f32 v85, v80, v81
	global_store_dwordx4 v[12:13], v[82:85], off
	v_cvt_pk_bf16_f32 v74, v74, v75
	v_cvt_pk_bf16_f32 v75, v76, v77
	v_cvt_pk_bf16_f32 v76, v70, v71
	v_cvt_pk_bf16_f32 v77, v72, v73
	global_store_dwordx4 v[12:13], v[74:77], off offset:256
	v_lshl_add_u64 v[12:13], v[12:13], 0, s[12:13]
	ds_read_b128 v[136:139], v10 offset:1024
	ds_read_b128 v[140:143], v10 offset:1280
	ds_read_b128 v[144:147], v10 offset:1536
	ds_read_b128 v[148:151], v10 offset:1792
	s_waitcnt lgkmcnt(0)
; #define LAS __attribute__((address_space(3)))
; __device__ __forceinline__ unsigned cvt_pk_bf16(float lo, float hi) { unsigned r; asm volatile("v_cvt_pk_bf16_f32 %0, %1, %2" : "=v"(r) : "v"(lo), "v"(hi)); return r; }
; __device__ __forceinline__ void epi_softmax(const f32x4 (&acc)[2][2][4][2], const Unit& u, char* Cb, unsigned cZ1, unsigned cZ2, int ldc, LAS float* rs, int wr, int wc, int fr, int fq) {
;     ...
;         for (int m = 0; m < 4; ++m) {
;             const f32x4 t = *(const LAS f32x4*)&rs[(wr * 128 + ai * 64 + m * 16 + fr) << 2];
;             const float lg = __logf(t[0] + t[1] + t[2] + t[3]);
;             bf16_t* rowp = base + (long)(ai * HALF + m * 16) * ldc;
; #pragma unroll
;             for (int bj = 0; bj < 2; ++bj) { f32x4 v0, v1;
; #pragma unroll
;                 for (int j = 0; j < 4; ++j) { v0[j] = __expf(acc[ai][bj][m][0][j] - lg); v1[j] = __expf(acc[ai][bj][m][1][j] - lg); }
;                 u32x4 w; w.x = cvt_pk_bf16(v0[0], v0[1]); w.y = cvt_pk_bf16(v0[2], v0[3]); w.z = cvt_pk_bf16(v1[0], v1[1]); w.w = cvt_pk_bf16(v1[2], v1[3]);
;                 *(u32x4*)(rowp + bj * HALF) = w; } }
	v_add_f32_e32 v136, v136, v137
	v_add_f32_e32 v136, v138, v136
	v_add_f32_e32 v136, v139, v136
	v_add_f32_e32 v140, v140, v141
	v_add_f32_e32 v140, v142, v140
	v_add_f32_e32 v140, v143, v140
	v_add_f32_e32 v144, v144, v145
	v_add_f32_e32 v144, v146, v144
	v_add_f32_e32 v144, v147, v144
	v_add_f32_e32 v148, v148, v149
	v_add_f32_e32 v148, v150, v148
	v_add_f32_e32 v148, v151, v148
	v_rcp_f32_e32 v152, v136
	v_rcp_f32_e32 v153, v140
	v_rcp_f32_e32 v154, v144
	v_rcp_f32_e32 v155, v148
	s_nop 0
	v_mul_f32_e32 v66, v66, v152
	v_mul_f32_e32 v67, v67, v152
	v_mul_f32_e32 v68, v68, v152
	v_mul_f32_e32 v69, v69, v152
	v_mul_f32_e32 v62, v62, v152
	v_mul_f32_e32 v63, v63, v152
	v_mul_f32_e32 v64, v64, v152
	v_mul_f32_e32 v65, v65, v152
	v_mul_f32_e32 v58, v58, v152
	v_mul_f32_e32 v59, v59, v152
	v_mul_f32_e32 v60, v60, v152
	v_mul_f32_e32 v61, v61, v152
	v_mul_f32_e32 v54, v54, v152
	v_mul_f32_e32 v55, v55, v152
	v_mul_f32_e32 v56, v56, v152
	v_mul_f32_e32 v57, v57, v152
	v_cvt_pk_bf16_f32 v66, v66, v67
	v_cvt_pk_bf16_f32 v67, v68, v69
	v_cvt_pk_bf16_f32 v68, v62, v63
	v_cvt_pk_bf16_f32 v69, v64, v65
	global_store_dwordx4 v[12:13], v[66:69], off
	v_cvt_pk_bf16_f32 v58, v58, v59
	v_cvt_pk_bf16_f32 v59, v60, v61
	v_cvt_pk_bf16_f32 v60, v54, v55
	v_cvt_pk_bf16_f32 v61, v56, v57
	global_store_dwordx4 v[12:13], v[58:61], off offset:256
	v_lshl_add_u64 v[12:13], v[12:13], 0, s[8:9]
	v_mul_f32_e32 v50, v50, v153
	v_mul_f32_e32 v51, v51, v153
	v_mul_f32_e32 v52, v52, v153
	v_mul_f32_e32 v53, v53, v153
	v_mul_f32_e32 v46, v46, v153
	v_mul_f32_e32 v47, v47, v153
	v_mul_f32_e32 v48, v48, v153
	v_mul_f32_e32 v49, v49, v153
	v_mul_f32_e32 v42, v42, v153
	v_mul_f32_e32 v43, v43, v153
	v_mul_f32_e32 v44, v44, v153
	v_mul_f32_e32 v45, v45, v153
	v_mul_f32_e32 v38, v38, v153
	v_mul_f32_e32 v39, v39, v153
	v_mul_f32_e32 v40, v40, v153
	v_mul_f32_e32 v41, v41, v153
	v_cvt_pk_bf16_f32 v50, v50, v51
	v_cvt_pk_bf16_f32 v51, v52, v53
	v_cvt_pk_bf16_f32 v52, v46, v47
	v_cvt_pk_bf16_f32 v53, v48, v49
	global_store_dwordx4 v[12:13], v[50:53], off
	v_cvt_pk_bf16_f32 v42, v42, v43
	v_cvt_pk_bf16_f32 v43, v44, v45
	v_cvt_pk_bf16_f32 v44, v38, v39
	v_cvt_pk_bf16_f32 v45, v40, v41
	global_store_dwordx4 v[12:13], v[42:45], off offset:256
	v_lshl_add_u64 v[12:13], v[12:13], 0, s[8:9]
	v_mul_f32_e32 v34, v34, v154
	v_mul_f32_e32 v35, v35, v154
	v_mul_f32_e32 v36, v36, v154
	v_mul_f32_e32 v37, v37, v154
	v_mul_f32_e32 v30, v30, v154
	v_mul_f32_e32 v31, v31, v154
	v_mul_f32_e32 v32, v32, v154
	v_mul_f32_e32 v33, v33, v154
	v_mul_f32_e32 v26, v26, v154
	v_mul_f32_e32 v27, v27, v154
	v_mul_f32_e32 v28, v28, v154
	v_mul_f32_e32 v29, v29, v154
	v_mul_f32_e32 v22, v22, v154
	v_mul_f32_e32 v23, v23, v154
	v_mul_f32_e32 v24, v24, v154
	v_mul_f32_e32 v25, v25, v154
	v_cvt_pk_bf16_f32 v34, v34, v35
	v_cvt_pk_bf16_f32 v35, v36, v37
	v_cvt_pk_bf16_f32 v36, v30, v31
	v_cvt_pk_bf16_f32 v37, v32, v33
	global_store_dwordx4 v[12:13], v[34:37], off
	v_cvt_pk_bf16_f32 v26, v26, v27
	v_cvt_pk_bf16_f32 v27, v28, v29
	v_cvt_pk_bf16_f32 v28, v22, v23
	v_cvt_pk_bf16_f32 v29, v24, v25
	global_store_dwordx4 v[12:13], v[26:29], off offset:256
	v_lshl_add_u64 v[12:13], v[12:13], 0, s[8:9]
	v_mul_f32_e32 v18, v18, v155
	v_mul_f32_e32 v19, v19, v155
	v_mul_f32_e32 v20, v20, v155
	v_mul_f32_e32 v21, v21, v155
	v_mul_f32_e32 v14, v14, v155
	v_mul_f32_e32 v15, v15, v155
	v_mul_f32_e32 v16, v16, v155
	v_mul_f32_e32 v17, v17, v155
	v_mul_f32_e32 v4, v4, v155
	v_mul_f32_e32 v5, v5, v155
	v_mul_f32_e32 v6, v6, v155
	v_mul_f32_e32 v7, v7, v155
	v_mul_f32_e32 v0, v0, v155
	v_mul_f32_e32 v1, v1, v155
	v_mul_f32_e32 v2, v2, v155
	v_mul_f32_e32 v3, v3, v155
	v_cvt_pk_bf16_f32 v18, v18, v19
	v_cvt_pk_bf16_f32 v19, v20, v21
	v_cvt_pk_bf16_f32 v20, v14, v15
	v_cvt_pk_bf16_f32 v21, v16, v17
	global_store_dwordx4 v[12:13], v[18:21], off
	v_cvt_pk_bf16_f32 v4, v4, v5
	v_cvt_pk_bf16_f32 v5, v6, v7
	v_cvt_pk_bf16_f32 v6, v0, v1
	v_cvt_pk_bf16_f32 v7, v2, v3
	global_store_dwordx4 v[12:13], v[4:7], off offset:256
